# strategy 4: one static s_setprio 1 for the younger wave half (waves 4-7) during the P2 FoX/HGRN2 units
# baseline (speedup 1.0000x reference)
.LBB0_256:
	s_mov_b32 s98, 0
	s_cmp_ge_u32 s33, 0x100
	s_cbranch_scc0 .Lprio_skip
	s_setprio 1
.Lprio_skip:
	s_cmp_lg_u32 s27, 2
	s_cselect_b64 s[0:1], -1, 0
	s_waitcnt lgkmcnt(0)
	s_xor_b64 s[54:55], s[4:5], -1
	s_and_b64 s[0:1], s[54:55], s[0:1]
	v_writelane_b32 v255, s54, 1
	s_and_b64 vcc, exec, s[0:1]
	s_nop 0
	v_writelane_b32 v255, s55, 2
	s_cbranch_vccnz .LBB0_590

.LBB0_537:
	s_setprio 0
	s_cmpk_ge_u32 s98, 0x1000
	s_cbranch_scc1 .Lp0b_ret_exit
	s_movk_i32 s98, 0x1000
	s_or_b32 s99, s99, 12
	s_branch .Lp0b_call
